# v67: v65 + the lq0 workgroup of each XCD issues an early L2 write-back when it arrives at a group-wide seam (before polling), so the final write-back has less to flush
# baseline (speedup 1.0000x reference)
.Lhb_lead_g1:
	buffer_wbl2 sc1
	s_mov_b64 exec, -1
	v_mbcnt_lo_u32_b32 v4, -1, 0
	v_mbcnt_hi_u32_b32 v4, -1, v4
	v_lshl_add_u32 v4, v4, 2, s99
	v_mov_b32_e32 v5, 0
